# GEMM K-loop: per-phase counted DMA waits + staged lgkm waits in MMA blocks + peeled first iteration (C=0, no accumulator zeroing), stacked on the aligned version
# speedup vs baseline: 1.0177x; 1.0151x over previous
.LBB0_140:
	s_add_u32 s0, s70, 0x80
	s_addc_u32 s1, s71, 0
	s_add_u32 s70, s68, 0x100
	s_addc_u32 s71, s69, 0
	s_mov_b32 s40, 0
	s_add_i32 s72, s40, 2
	s_add_u32 s68, s0, 0x80
	s_addc_u32 s41, s1, 0
	s_add_i32 s73, 0, 0x10000
	v_add_u32_e32 v140, s73, v183
	ds_read_b128 v[128:131], v140
	ds_read_b128 v[132:135], v140 offset:1024
	ds_read_b128 v[136:139], v140 offset:2048
	ds_read_b128 v[140:143], v140 offset:3072
	s_cmp_eq_u32 s10, s40
	s_cselect_b32 s40, s64, s68
	s_cselect_b32 s41, s65, s41
	s_cselect_b32 s69, s67, s71
	s_cselect_b32 s68, s66, s70
	v_lshl_add_u64 v[176:177], s[0:1], 0, v[192:193]
	s_add_i32 m0, s76, 0xc000
	ds_read_b128 v[144:147], v239
	ds_read_b128 v[148:151], v239 offset:1024
	ds_read_b128 v[152:155], v239 offset:2048
	ds_read_b128 v[156:159], v239 offset:3072
	ds_read_b128 v[160:163], v239 offset:4096
	ds_read_b128 v[164:167], v239 offset:5120
	ds_read_b128 v[168:171], v239 offset:6144
	ds_read_b128 v[172:175], v239 offset:7168
	global_load_lds_dwordx4 v[176:177], off
	v_lshl_add_u64 v[176:177], s[0:1], 0, v[194:195]
	s_add_i32 m0, s76, 0xe000
	s_nop 0
	global_load_lds_dwordx4 v[176:177], off
	s_waitcnt lgkmcnt(8)
	s_waitcnt vmcnt(10)
	s_barrier
	s_waitcnt lgkmcnt(7)
	v_mfma_f32_16x16x32_bf16 v[124:127], v[128:131], v[144:147], 0
	v_mfma_f32_16x16x32_bf16 v[116:119], v[136:139], v[144:147], 0
	s_waitcnt lgkmcnt(5)
	v_mfma_f32_16x16x32_bf16 v[108:111], v[128:131], v[152:155], 0
	v_mfma_f32_16x16x32_bf16 v[100:103], v[136:139], v[152:155], 0
	s_waitcnt lgkmcnt(3)
	v_mfma_f32_16x16x32_bf16 v[92:95], v[128:131], v[160:163], 0
	v_mfma_f32_16x16x32_bf16 v[84:87], v[136:139], v[160:163], 0
	s_waitcnt lgkmcnt(1)
	v_mfma_f32_16x16x32_bf16 v[76:79], v[128:131], v[168:171], 0
	v_mfma_f32_16x16x32_bf16 v[68:71], v[136:139], v[168:171], 0
	v_mfma_f32_16x16x32_bf16 v[124:127], v[132:135], v[148:151], v[124:127]
	v_mfma_f32_16x16x32_bf16 v[116:119], v[140:143], v[148:151], v[116:119]
	v_mfma_f32_16x16x32_bf16 v[108:111], v[132:135], v[156:159], v[108:111]
	v_mfma_f32_16x16x32_bf16 v[100:103], v[140:143], v[156:159], v[100:103]
	v_mfma_f32_16x16x32_bf16 v[92:95], v[132:135], v[164:167], v[92:95]
	v_mfma_f32_16x16x32_bf16 v[84:87], v[140:143], v[164:167], v[84:87]
	s_waitcnt lgkmcnt(0)
	v_mfma_f32_16x16x32_bf16 v[76:79], v[132:135], v[172:175], v[76:79]
	v_mfma_f32_16x16x32_bf16 v[68:71], v[140:143], v[172:175], v[68:71]
	s_barrier
	s_add_i32 s80, 0, 0x14000
	s_add_i32 s73, s73, s33
	v_add_u32_e32 v204, s80, v183
	v_lshl_add_u64 v[208:209], s[68:69], 0, v[186:187]
	s_mov_b32 m0, s73
	ds_read_b128 v[176:179], v204
	ds_read_b128 v[196:199], v204 offset:1024
	ds_read_b128 v[200:203], v204 offset:2048
	ds_read_b128 v[204:207], v204 offset:3072
	global_load_lds_dwordx4 v[208:209], off
	v_lshl_add_u64 v[210:211], s[68:69], 0, v[190:191]
	s_add_i32 m0, s73, 0x2000
	s_nop 0
	global_load_lds_dwordx4 v[210:211], off
	s_waitcnt vmcnt(10)
	s_barrier
	s_waitcnt lgkmcnt(3)
	v_mfma_f32_16x16x32_bf16 v[120:123], v[176:179], v[144:147], 0
	s_waitcnt lgkmcnt(1)
	v_mfma_f32_16x16x32_bf16 v[112:115], v[200:203], v[144:147], 0
	v_mfma_f32_16x16x32_bf16 v[104:107], v[176:179], v[152:155], 0
	v_mfma_f32_16x16x32_bf16 v[96:99], v[200:203], v[152:155], 0
	v_mfma_f32_16x16x32_bf16 v[88:91], v[176:179], v[160:163], 0
	v_mfma_f32_16x16x32_bf16 v[80:83], v[200:203], v[160:163], 0
	v_mfma_f32_16x16x32_bf16 v[72:75], v[176:179], v[168:171], 0
	v_mfma_f32_16x16x32_bf16 v[64:67], v[200:203], v[168:171], 0
	v_mfma_f32_16x16x32_bf16 v[120:123], v[196:199], v[148:151], v[120:123]
	s_waitcnt lgkmcnt(0)
	v_mfma_f32_16x16x32_bf16 v[112:115], v[204:207], v[148:151], v[112:115]
	v_mfma_f32_16x16x32_bf16 v[104:107], v[196:199], v[156:159], v[104:107]
	v_mfma_f32_16x16x32_bf16 v[96:99], v[204:207], v[156:159], v[96:99]
	v_mfma_f32_16x16x32_bf16 v[88:91], v[196:199], v[164:167], v[88:91]
	v_mfma_f32_16x16x32_bf16 v[80:83], v[204:207], v[164:167], v[80:83]
	v_mfma_f32_16x16x32_bf16 v[72:75], v[196:199], v[172:175], v[72:75]
	v_mfma_f32_16x16x32_bf16 v[64:67], v[204:207], v[172:175], v[64:67]
	s_mov_b32 m0, s76
	v_lshl_add_u64 v[212:213], s[40:41], 0, v[184:185]
	s_barrier
	ds_read_b128 v[144:147], v239 offset:16384
	ds_read_b128 v[148:151], v239 offset:17408
	ds_read_b128 v[152:155], v239 offset:18432
	ds_read_b128 v[156:159], v239 offset:19456
	ds_read_b128 v[160:163], v239 offset:20480
	ds_read_b128 v[164:167], v239 offset:21504
	ds_read_b128 v[168:171], v239 offset:22528
	ds_read_b128 v[172:175], v239 offset:23552
	global_load_lds_dwordx4 v[212:213], off
	v_lshl_add_u64 v[214:215], s[40:41], 0, v[188:189]
	s_mov_b32 m0, s4
	s_nop 0
	global_load_lds_dwordx4 v[214:215], off
	s_barrier
	s_waitcnt lgkmcnt(7)
	v_mfma_f32_16x16x32_bf16 v[60:63], v[128:131], v[144:147], 0
	v_mfma_f32_16x16x32_bf16 v[52:55], v[136:139], v[144:147], 0
	s_waitcnt lgkmcnt(5)
	v_mfma_f32_16x16x32_bf16 v[44:47], v[128:131], v[152:155], 0
	v_mfma_f32_16x16x32_bf16 v[36:39], v[136:139], v[152:155], 0
	s_waitcnt lgkmcnt(3)
	v_mfma_f32_16x16x32_bf16 v[28:31], v[128:131], v[160:163], 0
	v_mfma_f32_16x16x32_bf16 v[20:23], v[136:139], v[160:163], 0
	s_waitcnt lgkmcnt(1)
	v_mfma_f32_16x16x32_bf16 v[12:15], v[128:131], v[168:171], 0
	v_mfma_f32_16x16x32_bf16 v[4:7], v[136:139], v[168:171], 0
	v_mfma_f32_16x16x32_bf16 v[60:63], v[132:135], v[148:151], v[60:63]
	v_mfma_f32_16x16x32_bf16 v[52:55], v[140:143], v[148:151], v[52:55]
	v_mfma_f32_16x16x32_bf16 v[44:47], v[132:135], v[156:159], v[44:47]
	v_mfma_f32_16x16x32_bf16 v[36:39], v[140:143], v[156:159], v[36:39]
	v_mfma_f32_16x16x32_bf16 v[28:31], v[132:135], v[164:167], v[28:31]
	v_mfma_f32_16x16x32_bf16 v[20:23], v[140:143], v[164:167], v[20:23]
	s_waitcnt lgkmcnt(0)
	v_mfma_f32_16x16x32_bf16 v[12:15], v[132:135], v[172:175], v[12:15]
	v_mfma_f32_16x16x32_bf16 v[4:7], v[140:143], v[172:175], v[4:7]
	s_barrier
	s_add_u32 s68, s68, s98
	s_addc_u32 s69, s69, 0
	s_add_i32 s73, s80, s33
	v_lshl_add_u64 v[216:217], s[68:69], 0, v[186:187]
	s_mov_b32 m0, s73
	v_lshl_add_u64 v[218:219], s[68:69], 0, v[190:191]
	global_load_lds_dwordx4 v[216:217], off
	s_add_i32 m0, s73, 0x2000
	s_nop 0
	global_load_lds_dwordx4 v[218:219], off
	s_waitcnt vmcnt(10)
	s_barrier
	v_mfma_f32_16x16x32_bf16 v[56:59], v[176:179], v[144:147], 0
	v_mfma_f32_16x16x32_bf16 v[48:51], v[200:203], v[144:147], 0
	v_mfma_f32_16x16x32_bf16 v[40:43], v[176:179], v[152:155], 0
	v_mfma_f32_16x16x32_bf16 v[32:35], v[200:203], v[152:155], 0
	v_mfma_f32_16x16x32_bf16 v[24:27], v[176:179], v[160:163], 0
	v_mfma_f32_16x16x32_bf16 v[16:19], v[200:203], v[160:163], 0
	v_mfma_f32_16x16x32_bf16 v[8:11], v[176:179], v[168:171], 0
	v_mfma_f32_16x16x32_bf16 v[0:3], v[200:203], v[168:171], 0
	v_mfma_f32_16x16x32_bf16 v[56:59], v[196:199], v[148:151], v[56:59]
	v_mfma_f32_16x16x32_bf16 v[48:51], v[204:207], v[148:151], v[48:51]
	v_mfma_f32_16x16x32_bf16 v[40:43], v[196:199], v[156:159], v[40:43]
	v_mfma_f32_16x16x32_bf16 v[32:35], v[204:207], v[156:159], v[32:35]
	v_mfma_f32_16x16x32_bf16 v[24:27], v[196:199], v[164:167], v[24:27]
	v_mfma_f32_16x16x32_bf16 v[16:19], v[204:207], v[164:167], v[16:19]
	v_mfma_f32_16x16x32_bf16 v[8:11], v[196:199], v[172:175], v[8:11]
	v_mfma_f32_16x16x32_bf16 v[0:3], v[204:207], v[172:175], v[0:3]
	s_add_i32 s68, 0, 0x18000
	v_add_u32_e32 v140, s68, v183
	s_barrier
	ds_read_b128 v[128:131], v140
	ds_read_b128 v[132:135], v140 offset:1024
	ds_read_b128 v[136:139], v140 offset:2048
	ds_read_b128 v[140:143], v140 offset:3072
	s_add_u32 s40, s40, s98
	s_addc_u32 s41, s41, 0
	s_mov_b32 m0, s5
	v_lshl_add_u64 v[176:177], s[40:41], 0, v[184:185]
	ds_read_b128 v[144:147], v239 offset:32768
	ds_read_b128 v[148:151], v239 offset:33792
	ds_read_b128 v[152:155], v239 offset:34816
	ds_read_b128 v[156:159], v239 offset:35840
	ds_read_b128 v[160:163], v239 offset:36864
	ds_read_b128 v[164:167], v239 offset:37888
	ds_read_b128 v[168:171], v239 offset:38912
	ds_read_b128 v[172:175], v239 offset:39936
	global_load_lds_dwordx4 v[176:177], off
	v_lshl_add_u64 v[176:177], s[40:41], 0, v[188:189]
	s_mov_b32 m0, s6
	s_nop 0
	global_load_lds_dwordx4 v[176:177], off
	s_waitcnt lgkmcnt(8)
	s_waitcnt vmcnt(10)
	s_barrier
	s_waitcnt lgkmcnt(7)
	v_mfma_f32_16x16x32_bf16 v[124:127], v[128:131], v[144:147], v[124:127]
	v_mfma_f32_16x16x32_bf16 v[116:119], v[136:139], v[144:147], v[116:119]
	s_waitcnt lgkmcnt(5)
	v_mfma_f32_16x16x32_bf16 v[108:111], v[128:131], v[152:155], v[108:111]
	v_mfma_f32_16x16x32_bf16 v[100:103], v[136:139], v[152:155], v[100:103]
	s_waitcnt lgkmcnt(3)
	v_mfma_f32_16x16x32_bf16 v[92:95], v[128:131], v[160:163], v[92:95]
	v_mfma_f32_16x16x32_bf16 v[84:87], v[136:139], v[160:163], v[84:87]
	s_waitcnt lgkmcnt(1)
	v_mfma_f32_16x16x32_bf16 v[76:79], v[128:131], v[168:171], v[76:79]
	v_mfma_f32_16x16x32_bf16 v[68:71], v[136:139], v[168:171], v[68:71]
	v_mfma_f32_16x16x32_bf16 v[124:127], v[132:135], v[148:151], v[124:127]
	v_mfma_f32_16x16x32_bf16 v[116:119], v[140:143], v[148:151], v[116:119]
	v_mfma_f32_16x16x32_bf16 v[108:111], v[132:135], v[156:159], v[108:111]
	v_mfma_f32_16x16x32_bf16 v[100:103], v[140:143], v[156:159], v[100:103]
	v_mfma_f32_16x16x32_bf16 v[92:95], v[132:135], v[164:167], v[92:95]
	v_mfma_f32_16x16x32_bf16 v[84:87], v[140:143], v[164:167], v[84:87]
	s_waitcnt lgkmcnt(0)
	v_mfma_f32_16x16x32_bf16 v[76:79], v[132:135], v[172:175], v[76:79]
	v_mfma_f32_16x16x32_bf16 v[68:71], v[140:143], v[172:175], v[68:71]
	s_barrier
	s_add_i32 s40, 0, 0x1c000
	s_add_i32 s41, s68, s33
	v_add_u32_e32 v204, s40, v183
	v_lshl_add_u64 v[208:209], v[208:209], 0, s[96:97]
	s_mov_b32 m0, s41
	ds_read_b128 v[176:179], v204
	ds_read_b128 v[196:199], v204 offset:1024
	ds_read_b128 v[200:203], v204 offset:2048
	ds_read_b128 v[204:207], v204 offset:3072
	global_load_lds_dwordx4 v[208:209], off
	v_lshl_add_u64 v[208:209], v[210:211], 0, s[96:97]
	s_add_i32 m0, s41, 0x2000
	s_nop 0
	global_load_lds_dwordx4 v[208:209], off
	s_waitcnt vmcnt(10)
	s_barrier
	s_waitcnt lgkmcnt(3)
	v_mfma_f32_16x16x32_bf16 v[120:123], v[176:179], v[144:147], v[120:123]
	s_waitcnt lgkmcnt(1)
	v_mfma_f32_16x16x32_bf16 v[112:115], v[200:203], v[144:147], v[112:115]
	v_mfma_f32_16x16x32_bf16 v[104:107], v[176:179], v[152:155], v[104:107]
	v_mfma_f32_16x16x32_bf16 v[96:99], v[200:203], v[152:155], v[96:99]
	v_mfma_f32_16x16x32_bf16 v[88:91], v[176:179], v[160:163], v[88:91]
	v_mfma_f32_16x16x32_bf16 v[80:83], v[200:203], v[160:163], v[80:83]
	v_mfma_f32_16x16x32_bf16 v[72:75], v[176:179], v[168:171], v[72:75]
	v_mfma_f32_16x16x32_bf16 v[64:67], v[200:203], v[168:171], v[64:67]
	v_mfma_f32_16x16x32_bf16 v[120:123], v[196:199], v[148:151], v[120:123]
	s_waitcnt lgkmcnt(0)
	v_mfma_f32_16x16x32_bf16 v[112:115], v[204:207], v[148:151], v[112:115]
	v_mfma_f32_16x16x32_bf16 v[104:107], v[196:199], v[156:159], v[104:107]
	v_mfma_f32_16x16x32_bf16 v[96:99], v[204:207], v[156:159], v[96:99]
	v_mfma_f32_16x16x32_bf16 v[88:91], v[196:199], v[164:167], v[88:91]
	v_mfma_f32_16x16x32_bf16 v[80:83], v[204:207], v[164:167], v[80:83]
	v_mfma_f32_16x16x32_bf16 v[72:75], v[196:199], v[172:175], v[72:75]
	v_mfma_f32_16x16x32_bf16 v[64:67], v[204:207], v[172:175], v[64:67]
	s_mov_b32 m0, s8
	v_lshl_add_u64 v[208:209], v[212:213], 0, s[96:97]
	s_barrier
	ds_read_b128 v[144:147], v239 offset:49152
	ds_read_b128 v[148:151], v239 offset:50176
	ds_read_b128 v[152:155], v239 offset:51200
	ds_read_b128 v[156:159], v239 offset:52224
	ds_read_b128 v[160:163], v239 offset:53248
	ds_read_b128 v[164:167], v239 offset:54272
	ds_read_b128 v[168:171], v239 offset:55296
	ds_read_b128 v[172:175], v239 offset:56320
	global_load_lds_dwordx4 v[208:209], off
	v_lshl_add_u64 v[208:209], v[214:215], 0, s[96:97]
	s_mov_b32 m0, s9
	s_nop 0
	global_load_lds_dwordx4 v[208:209], off
	s_barrier
	s_waitcnt lgkmcnt(7)
	v_mfma_f32_16x16x32_bf16 v[60:63], v[128:131], v[144:147], v[60:63]
	v_mfma_f32_16x16x32_bf16 v[52:55], v[136:139], v[144:147], v[52:55]
	s_waitcnt lgkmcnt(5)
	v_mfma_f32_16x16x32_bf16 v[44:47], v[128:131], v[152:155], v[44:47]
	v_mfma_f32_16x16x32_bf16 v[36:39], v[136:139], v[152:155], v[36:39]
	s_waitcnt lgkmcnt(3)
	v_mfma_f32_16x16x32_bf16 v[28:31], v[128:131], v[160:163], v[28:31]
	v_mfma_f32_16x16x32_bf16 v[20:23], v[136:139], v[160:163], v[20:23]
	s_waitcnt lgkmcnt(1)
	v_mfma_f32_16x16x32_bf16 v[12:15], v[128:131], v[168:171], v[12:15]
	v_mfma_f32_16x16x32_bf16 v[4:7], v[136:139], v[168:171], v[4:7]
	v_mfma_f32_16x16x32_bf16 v[60:63], v[132:135], v[148:151], v[60:63]
	v_mfma_f32_16x16x32_bf16 v[52:55], v[140:143], v[148:151], v[52:55]
	v_mfma_f32_16x16x32_bf16 v[44:47], v[132:135], v[156:159], v[44:47]
	v_mfma_f32_16x16x32_bf16 v[36:39], v[140:143], v[156:159], v[36:39]
	v_mfma_f32_16x16x32_bf16 v[28:31], v[132:135], v[164:167], v[28:31]
	v_mfma_f32_16x16x32_bf16 v[20:23], v[140:143], v[164:167], v[20:23]
	s_waitcnt lgkmcnt(0)
	v_mfma_f32_16x16x32_bf16 v[12:15], v[132:135], v[172:175], v[12:15]
	v_mfma_f32_16x16x32_bf16 v[4:7], v[140:143], v[172:175], v[4:7]
	s_barrier
	s_add_i32 s40, s40, s33
	v_lshl_add_u64 v[128:129], v[216:217], 0, s[96:97]
	s_mov_b32 m0, s40
	s_nop 0
	global_load_lds_dwordx4 v[128:129], off
	v_lshl_add_u64 v[128:129], v[218:219], 0, s[96:97]
	s_add_i32 m0, s40, 0x2000
	s_nop 0
	global_load_lds_dwordx4 v[128:129], off
	s_waitcnt vmcnt(10)
	s_barrier
	v_mfma_f32_16x16x32_bf16 v[56:59], v[176:179], v[144:147], v[56:59]
	v_mfma_f32_16x16x32_bf16 v[48:51], v[200:203], v[144:147], v[48:51]
	v_mfma_f32_16x16x32_bf16 v[40:43], v[176:179], v[152:155], v[40:43]
	v_mfma_f32_16x16x32_bf16 v[32:35], v[200:203], v[152:155], v[32:35]
	v_mfma_f32_16x16x32_bf16 v[24:27], v[176:179], v[160:163], v[24:27]
	v_mfma_f32_16x16x32_bf16 v[16:19], v[200:203], v[160:163], v[16:19]
	v_mfma_f32_16x16x32_bf16 v[8:11], v[176:179], v[168:171], v[8:11]
	v_mfma_f32_16x16x32_bf16 v[0:3], v[200:203], v[168:171], v[0:3]
	v_mfma_f32_16x16x32_bf16 v[56:59], v[196:199], v[148:151], v[56:59]
	v_mfma_f32_16x16x32_bf16 v[48:51], v[204:207], v[148:151], v[48:51]
	v_mfma_f32_16x16x32_bf16 v[40:43], v[196:199], v[156:159], v[40:43]
	v_mfma_f32_16x16x32_bf16 v[32:35], v[204:207], v[156:159], v[32:35]
	v_mfma_f32_16x16x32_bf16 v[24:27], v[196:199], v[164:167], v[24:27]
	v_mfma_f32_16x16x32_bf16 v[16:19], v[204:207], v[164:167], v[16:19]
	v_mfma_f32_16x16x32_bf16 v[8:11], v[196:199], v[172:175], v[8:11]
	v_mfma_f32_16x16x32_bf16 v[0:3], v[204:207], v[172:175], v[0:3]
	s_add_u32 s0, s0, 0x100
	s_addc_u32 s1, s1, 0
	s_add_u32 s70, s70, 0x100
	s_addc_u32 s71, s71, 0
	s_cmp_ge_u32 s72, s7
	s_mov_b32 s40, s72
	s_barrier
	s_cbranch_scc0 .LBB0_141
	s_branch .Lgemm_kloop_done
.LBB0_141:
	s_add_i32 s72, s40, 2
	s_add_u32 s68, s0, 0x80
	s_addc_u32 s41, s1, 0
	s_add_i32 s73, 0, 0x10000
	v_add_u32_e32 v140, s73, v183
	ds_read_b128 v[128:131], v140
	ds_read_b128 v[132:135], v140 offset:1024
	ds_read_b128 v[136:139], v140 offset:2048
	ds_read_b128 v[140:143], v140 offset:3072
	s_cmp_eq_u32 s10, s40
	s_cselect_b32 s40, s64, s68
	s_cselect_b32 s41, s65, s41
	s_cselect_b32 s69, s67, s71
	s_cselect_b32 s68, s66, s70
	v_lshl_add_u64 v[176:177], s[0:1], 0, v[192:193]
	s_add_i32 m0, s76, 0xc000
	ds_read_b128 v[144:147], v239
	ds_read_b128 v[148:151], v239 offset:1024
	ds_read_b128 v[152:155], v239 offset:2048
	ds_read_b128 v[156:159], v239 offset:3072
	ds_read_b128 v[160:163], v239 offset:4096
	ds_read_b128 v[164:167], v239 offset:5120
	ds_read_b128 v[168:171], v239 offset:6144
	ds_read_b128 v[172:175], v239 offset:7168
	global_load_lds_dwordx4 v[176:177], off
	v_lshl_add_u64 v[176:177], s[0:1], 0, v[194:195]
	s_add_i32 m0, s76, 0xe000
	s_nop 0
	global_load_lds_dwordx4 v[176:177], off
	s_waitcnt lgkmcnt(8)
	s_waitcnt vmcnt(10)
	s_barrier
	s_waitcnt lgkmcnt(7)
	v_mfma_f32_16x16x32_bf16 v[124:127], v[128:131], v[144:147], v[124:127]
	v_mfma_f32_16x16x32_bf16 v[116:119], v[136:139], v[144:147], v[116:119]
	s_waitcnt lgkmcnt(5)
	v_mfma_f32_16x16x32_bf16 v[108:111], v[128:131], v[152:155], v[108:111]
	v_mfma_f32_16x16x32_bf16 v[100:103], v[136:139], v[152:155], v[100:103]
	s_waitcnt lgkmcnt(3)
	v_mfma_f32_16x16x32_bf16 v[92:95], v[128:131], v[160:163], v[92:95]
	v_mfma_f32_16x16x32_bf16 v[84:87], v[136:139], v[160:163], v[84:87]
	s_waitcnt lgkmcnt(1)
	v_mfma_f32_16x16x32_bf16 v[76:79], v[128:131], v[168:171], v[76:79]
	v_mfma_f32_16x16x32_bf16 v[68:71], v[136:139], v[168:171], v[68:71]
	v_mfma_f32_16x16x32_bf16 v[124:127], v[132:135], v[148:151], v[124:127]
	v_mfma_f32_16x16x32_bf16 v[116:119], v[140:143], v[148:151], v[116:119]
	v_mfma_f32_16x16x32_bf16 v[108:111], v[132:135], v[156:159], v[108:111]
	v_mfma_f32_16x16x32_bf16 v[100:103], v[140:143], v[156:159], v[100:103]
	v_mfma_f32_16x16x32_bf16 v[92:95], v[132:135], v[164:167], v[92:95]
	v_mfma_f32_16x16x32_bf16 v[84:87], v[140:143], v[164:167], v[84:87]
	s_waitcnt lgkmcnt(0)
	v_mfma_f32_16x16x32_bf16 v[76:79], v[132:135], v[172:175], v[76:79]
	v_mfma_f32_16x16x32_bf16 v[68:71], v[140:143], v[172:175], v[68:71]
	s_barrier
	s_add_i32 s80, 0, 0x14000
	s_add_i32 s73, s73, s33
	v_add_u32_e32 v204, s80, v183
	v_lshl_add_u64 v[208:209], s[68:69], 0, v[186:187]
	s_mov_b32 m0, s73
	ds_read_b128 v[176:179], v204
	ds_read_b128 v[196:199], v204 offset:1024
	ds_read_b128 v[200:203], v204 offset:2048
	ds_read_b128 v[204:207], v204 offset:3072
	global_load_lds_dwordx4 v[208:209], off
	v_lshl_add_u64 v[210:211], s[68:69], 0, v[190:191]
	s_add_i32 m0, s73, 0x2000
	s_nop 0
	global_load_lds_dwordx4 v[210:211], off
	s_waitcnt vmcnt(10)
	s_barrier
	s_waitcnt lgkmcnt(3)
	v_mfma_f32_16x16x32_bf16 v[120:123], v[176:179], v[144:147], v[120:123]
	s_waitcnt lgkmcnt(1)
	v_mfma_f32_16x16x32_bf16 v[112:115], v[200:203], v[144:147], v[112:115]
	v_mfma_f32_16x16x32_bf16 v[104:107], v[176:179], v[152:155], v[104:107]
	v_mfma_f32_16x16x32_bf16 v[96:99], v[200:203], v[152:155], v[96:99]
	v_mfma_f32_16x16x32_bf16 v[88:91], v[176:179], v[160:163], v[88:91]
	v_mfma_f32_16x16x32_bf16 v[80:83], v[200:203], v[160:163], v[80:83]
	v_mfma_f32_16x16x32_bf16 v[72:75], v[176:179], v[168:171], v[72:75]
	v_mfma_f32_16x16x32_bf16 v[64:67], v[200:203], v[168:171], v[64:67]
	v_mfma_f32_16x16x32_bf16 v[120:123], v[196:199], v[148:151], v[120:123]
	s_waitcnt lgkmcnt(0)
	v_mfma_f32_16x16x32_bf16 v[112:115], v[204:207], v[148:151], v[112:115]
	v_mfma_f32_16x16x32_bf16 v[104:107], v[196:199], v[156:159], v[104:107]
	v_mfma_f32_16x16x32_bf16 v[96:99], v[204:207], v[156:159], v[96:99]
	v_mfma_f32_16x16x32_bf16 v[88:91], v[196:199], v[164:167], v[88:91]
	v_mfma_f32_16x16x32_bf16 v[80:83], v[204:207], v[164:167], v[80:83]
	v_mfma_f32_16x16x32_bf16 v[72:75], v[196:199], v[172:175], v[72:75]
	v_mfma_f32_16x16x32_bf16 v[64:67], v[204:207], v[172:175], v[64:67]
	s_mov_b32 m0, s76
	v_lshl_add_u64 v[212:213], s[40:41], 0, v[184:185]
	s_barrier
	ds_read_b128 v[144:147], v239 offset:16384
	ds_read_b128 v[148:151], v239 offset:17408
	ds_read_b128 v[152:155], v239 offset:18432
	ds_read_b128 v[156:159], v239 offset:19456
	ds_read_b128 v[160:163], v239 offset:20480
	ds_read_b128 v[164:167], v239 offset:21504
	ds_read_b128 v[168:171], v239 offset:22528
	ds_read_b128 v[172:175], v239 offset:23552
	global_load_lds_dwordx4 v[212:213], off
	v_lshl_add_u64 v[214:215], s[40:41], 0, v[188:189]
	s_mov_b32 m0, s4
	s_nop 0
	global_load_lds_dwordx4 v[214:215], off
	s_barrier
	s_waitcnt lgkmcnt(7)
	v_mfma_f32_16x16x32_bf16 v[60:63], v[128:131], v[144:147], v[60:63]
	v_mfma_f32_16x16x32_bf16 v[52:55], v[136:139], v[144:147], v[52:55]
	s_waitcnt lgkmcnt(5)
	v_mfma_f32_16x16x32_bf16 v[44:47], v[128:131], v[152:155], v[44:47]
	v_mfma_f32_16x16x32_bf16 v[36:39], v[136:139], v[152:155], v[36:39]
	s_waitcnt lgkmcnt(3)
	v_mfma_f32_16x16x32_bf16 v[28:31], v[128:131], v[160:163], v[28:31]
	v_mfma_f32_16x16x32_bf16 v[20:23], v[136:139], v[160:163], v[20:23]
	s_waitcnt lgkmcnt(1)
	v_mfma_f32_16x16x32_bf16 v[12:15], v[128:131], v[168:171], v[12:15]
	v_mfma_f32_16x16x32_bf16 v[4:7], v[136:139], v[168:171], v[4:7]
	v_mfma_f32_16x16x32_bf16 v[60:63], v[132:135], v[148:151], v[60:63]
	v_mfma_f32_16x16x32_bf16 v[52:55], v[140:143], v[148:151], v[52:55]
	v_mfma_f32_16x16x32_bf16 v[44:47], v[132:135], v[156:159], v[44:47]
	v_mfma_f32_16x16x32_bf16 v[36:39], v[140:143], v[156:159], v[36:39]
	v_mfma_f32_16x16x32_bf16 v[28:31], v[132:135], v[164:167], v[28:31]
	v_mfma_f32_16x16x32_bf16 v[20:23], v[140:143], v[164:167], v[20:23]
	s_waitcnt lgkmcnt(0)
	v_mfma_f32_16x16x32_bf16 v[12:15], v[132:135], v[172:175], v[12:15]
	v_mfma_f32_16x16x32_bf16 v[4:7], v[140:143], v[172:175], v[4:7]
	s_barrier
	s_add_u32 s68, s68, s98
	s_addc_u32 s69, s69, 0
	s_add_i32 s73, s80, s33
	v_lshl_add_u64 v[216:217], s[68:69], 0, v[186:187]
	s_mov_b32 m0, s73
	v_lshl_add_u64 v[218:219], s[68:69], 0, v[190:191]
	global_load_lds_dwordx4 v[216:217], off
	s_add_i32 m0, s73, 0x2000
	s_nop 0
	global_load_lds_dwordx4 v[218:219], off
	s_waitcnt vmcnt(10)
	s_barrier
	v_mfma_f32_16x16x32_bf16 v[56:59], v[176:179], v[144:147], v[56:59]
	v_mfma_f32_16x16x32_bf16 v[48:51], v[200:203], v[144:147], v[48:51]
	v_mfma_f32_16x16x32_bf16 v[40:43], v[176:179], v[152:155], v[40:43]
	v_mfma_f32_16x16x32_bf16 v[32:35], v[200:203], v[152:155], v[32:35]
	v_mfma_f32_16x16x32_bf16 v[24:27], v[176:179], v[160:163], v[24:27]
	v_mfma_f32_16x16x32_bf16 v[16:19], v[200:203], v[160:163], v[16:19]
	v_mfma_f32_16x16x32_bf16 v[8:11], v[176:179], v[168:171], v[8:11]
	v_mfma_f32_16x16x32_bf16 v[0:3], v[200:203], v[168:171], v[0:3]
	v_mfma_f32_16x16x32_bf16 v[56:59], v[196:199], v[148:151], v[56:59]
	v_mfma_f32_16x16x32_bf16 v[48:51], v[204:207], v[148:151], v[48:51]
	v_mfma_f32_16x16x32_bf16 v[40:43], v[196:199], v[156:159], v[40:43]
	v_mfma_f32_16x16x32_bf16 v[32:35], v[204:207], v[156:159], v[32:35]
	v_mfma_f32_16x16x32_bf16 v[24:27], v[196:199], v[164:167], v[24:27]
	v_mfma_f32_16x16x32_bf16 v[16:19], v[204:207], v[164:167], v[16:19]
	v_mfma_f32_16x16x32_bf16 v[8:11], v[196:199], v[172:175], v[8:11]
	v_mfma_f32_16x16x32_bf16 v[0:3], v[204:207], v[172:175], v[0:3]
	s_add_i32 s68, 0, 0x18000
	v_add_u32_e32 v140, s68, v183
	s_barrier
	ds_read_b128 v[128:131], v140
	ds_read_b128 v[132:135], v140 offset:1024
	ds_read_b128 v[136:139], v140 offset:2048
	ds_read_b128 v[140:143], v140 offset:3072
	s_add_u32 s40, s40, s98
	s_addc_u32 s41, s41, 0
	s_mov_b32 m0, s5
	v_lshl_add_u64 v[176:177], s[40:41], 0, v[184:185]
	ds_read_b128 v[144:147], v239 offset:32768
	ds_read_b128 v[148:151], v239 offset:33792
	ds_read_b128 v[152:155], v239 offset:34816
	ds_read_b128 v[156:159], v239 offset:35840
	ds_read_b128 v[160:163], v239 offset:36864
	ds_read_b128 v[164:167], v239 offset:37888
	ds_read_b128 v[168:171], v239 offset:38912
	ds_read_b128 v[172:175], v239 offset:39936
	global_load_lds_dwordx4 v[176:177], off
	v_lshl_add_u64 v[176:177], s[40:41], 0, v[188:189]
	s_mov_b32 m0, s6
	s_nop 0
	global_load_lds_dwordx4 v[176:177], off
	s_waitcnt lgkmcnt(8)
	s_waitcnt vmcnt(10)
	s_barrier
	s_waitcnt lgkmcnt(7)
	v_mfma_f32_16x16x32_bf16 v[124:127], v[128:131], v[144:147], v[124:127]
	v_mfma_f32_16x16x32_bf16 v[116:119], v[136:139], v[144:147], v[116:119]
	s_waitcnt lgkmcnt(5)
	v_mfma_f32_16x16x32_bf16 v[108:111], v[128:131], v[152:155], v[108:111]
	v_mfma_f32_16x16x32_bf16 v[100:103], v[136:139], v[152:155], v[100:103]
	s_waitcnt lgkmcnt(3)
	v_mfma_f32_16x16x32_bf16 v[92:95], v[128:131], v[160:163], v[92:95]
	v_mfma_f32_16x16x32_bf16 v[84:87], v[136:139], v[160:163], v[84:87]
	s_waitcnt lgkmcnt(1)
	v_mfma_f32_16x16x32_bf16 v[76:79], v[128:131], v[168:171], v[76:79]
	v_mfma_f32_16x16x32_bf16 v[68:71], v[136:139], v[168:171], v[68:71]
	v_mfma_f32_16x16x32_bf16 v[124:127], v[132:135], v[148:151], v[124:127]
	v_mfma_f32_16x16x32_bf16 v[116:119], v[140:143], v[148:151], v[116:119]
	v_mfma_f32_16x16x32_bf16 v[108:111], v[132:135], v[156:159], v[108:111]
	v_mfma_f32_16x16x32_bf16 v[100:103], v[140:143], v[156:159], v[100:103]
	v_mfma_f32_16x16x32_bf16 v[92:95], v[132:135], v[164:167], v[92:95]
	v_mfma_f32_16x16x32_bf16 v[84:87], v[140:143], v[164:167], v[84:87]
	s_waitcnt lgkmcnt(0)
	v_mfma_f32_16x16x32_bf16 v[76:79], v[132:135], v[172:175], v[76:79]
	v_mfma_f32_16x16x32_bf16 v[68:71], v[140:143], v[172:175], v[68:71]
	s_barrier
	s_add_i32 s40, 0, 0x1c000
	s_add_i32 s41, s68, s33
	v_add_u32_e32 v204, s40, v183
	v_lshl_add_u64 v[208:209], v[208:209], 0, s[96:97]
	s_mov_b32 m0, s41
	ds_read_b128 v[176:179], v204
	ds_read_b128 v[196:199], v204 offset:1024
	ds_read_b128 v[200:203], v204 offset:2048
	ds_read_b128 v[204:207], v204 offset:3072
	global_load_lds_dwordx4 v[208:209], off
	v_lshl_add_u64 v[208:209], v[210:211], 0, s[96:97]
	s_add_i32 m0, s41, 0x2000
	s_nop 0
	global_load_lds_dwordx4 v[208:209], off
	s_waitcnt vmcnt(10)
	s_barrier
	s_waitcnt lgkmcnt(3)
	v_mfma_f32_16x16x32_bf16 v[120:123], v[176:179], v[144:147], v[120:123]
	s_waitcnt lgkmcnt(1)
	v_mfma_f32_16x16x32_bf16 v[112:115], v[200:203], v[144:147], v[112:115]
	v_mfma_f32_16x16x32_bf16 v[104:107], v[176:179], v[152:155], v[104:107]
	v_mfma_f32_16x16x32_bf16 v[96:99], v[200:203], v[152:155], v[96:99]
	v_mfma_f32_16x16x32_bf16 v[88:91], v[176:179], v[160:163], v[88:91]
	v_mfma_f32_16x16x32_bf16 v[80:83], v[200:203], v[160:163], v[80:83]
	v_mfma_f32_16x16x32_bf16 v[72:75], v[176:179], v[168:171], v[72:75]
	v_mfma_f32_16x16x32_bf16 v[64:67], v[200:203], v[168:171], v[64:67]
	v_mfma_f32_16x16x32_bf16 v[120:123], v[196:199], v[148:151], v[120:123]
	s_waitcnt lgkmcnt(0)
	v_mfma_f32_16x16x32_bf16 v[112:115], v[204:207], v[148:151], v[112:115]
	v_mfma_f32_16x16x32_bf16 v[104:107], v[196:199], v[156:159], v[104:107]
	v_mfma_f32_16x16x32_bf16 v[96:99], v[204:207], v[156:159], v[96:99]
	v_mfma_f32_16x16x32_bf16 v[88:91], v[196:199], v[164:167], v[88:91]
	v_mfma_f32_16x16x32_bf16 v[80:83], v[204:207], v[164:167], v[80:83]
	v_mfma_f32_16x16x32_bf16 v[72:75], v[196:199], v[172:175], v[72:75]
	v_mfma_f32_16x16x32_bf16 v[64:67], v[204:207], v[172:175], v[64:67]
	s_mov_b32 m0, s8
	v_lshl_add_u64 v[208:209], v[212:213], 0, s[96:97]
	s_barrier
	ds_read_b128 v[144:147], v239 offset:49152
	ds_read_b128 v[148:151], v239 offset:50176
	ds_read_b128 v[152:155], v239 offset:51200
	ds_read_b128 v[156:159], v239 offset:52224
	ds_read_b128 v[160:163], v239 offset:53248
	ds_read_b128 v[164:167], v239 offset:54272
	ds_read_b128 v[168:171], v239 offset:55296
	ds_read_b128 v[172:175], v239 offset:56320
	global_load_lds_dwordx4 v[208:209], off
	v_lshl_add_u64 v[208:209], v[214:215], 0, s[96:97]
	s_mov_b32 m0, s9
	s_nop 0
	global_load_lds_dwordx4 v[208:209], off
	s_barrier
	s_waitcnt lgkmcnt(7)
	v_mfma_f32_16x16x32_bf16 v[60:63], v[128:131], v[144:147], v[60:63]
	v_mfma_f32_16x16x32_bf16 v[52:55], v[136:139], v[144:147], v[52:55]
	s_waitcnt lgkmcnt(5)
	v_mfma_f32_16x16x32_bf16 v[44:47], v[128:131], v[152:155], v[44:47]
	v_mfma_f32_16x16x32_bf16 v[36:39], v[136:139], v[152:155], v[36:39]
	s_waitcnt lgkmcnt(3)
	v_mfma_f32_16x16x32_bf16 v[28:31], v[128:131], v[160:163], v[28:31]
	v_mfma_f32_16x16x32_bf16 v[20:23], v[136:139], v[160:163], v[20:23]
	s_waitcnt lgkmcnt(1)
	v_mfma_f32_16x16x32_bf16 v[12:15], v[128:131], v[168:171], v[12:15]
	v_mfma_f32_16x16x32_bf16 v[4:7], v[136:139], v[168:171], v[4:7]
	v_mfma_f32_16x16x32_bf16 v[60:63], v[132:135], v[148:151], v[60:63]
	v_mfma_f32_16x16x32_bf16 v[52:55], v[140:143], v[148:151], v[52:55]
	v_mfma_f32_16x16x32_bf16 v[44:47], v[132:135], v[156:159], v[44:47]
	v_mfma_f32_16x16x32_bf16 v[36:39], v[140:143], v[156:159], v[36:39]
	v_mfma_f32_16x16x32_bf16 v[28:31], v[132:135], v[164:167], v[28:31]
	v_mfma_f32_16x16x32_bf16 v[20:23], v[140:143], v[164:167], v[20:23]
	s_waitcnt lgkmcnt(0)
	v_mfma_f32_16x16x32_bf16 v[12:15], v[132:135], v[172:175], v[12:15]
	v_mfma_f32_16x16x32_bf16 v[4:7], v[140:143], v[172:175], v[4:7]
	s_barrier
	s_add_i32 s40, s40, s33
	v_lshl_add_u64 v[128:129], v[216:217], 0, s[96:97]
	s_mov_b32 m0, s40
	s_nop 0
	global_load_lds_dwordx4 v[128:129], off
	v_lshl_add_u64 v[128:129], v[218:219], 0, s[96:97]
	s_add_i32 m0, s40, 0x2000
	s_nop 0
	global_load_lds_dwordx4 v[128:129], off
	s_waitcnt vmcnt(10)
	s_barrier
	v_mfma_f32_16x16x32_bf16 v[56:59], v[176:179], v[144:147], v[56:59]
	v_mfma_f32_16x16x32_bf16 v[48:51], v[200:203], v[144:147], v[48:51]
	v_mfma_f32_16x16x32_bf16 v[40:43], v[176:179], v[152:155], v[40:43]
	v_mfma_f32_16x16x32_bf16 v[32:35], v[200:203], v[152:155], v[32:35]
	v_mfma_f32_16x16x32_bf16 v[24:27], v[176:179], v[160:163], v[24:27]
	v_mfma_f32_16x16x32_bf16 v[16:19], v[200:203], v[160:163], v[16:19]
	v_mfma_f32_16x16x32_bf16 v[8:11], v[176:179], v[168:171], v[8:11]
	v_mfma_f32_16x16x32_bf16 v[0:3], v[200:203], v[168:171], v[0:3]
	v_mfma_f32_16x16x32_bf16 v[56:59], v[196:199], v[148:151], v[56:59]
	v_mfma_f32_16x16x32_bf16 v[48:51], v[204:207], v[148:151], v[48:51]
	v_mfma_f32_16x16x32_bf16 v[40:43], v[196:199], v[156:159], v[40:43]
	v_mfma_f32_16x16x32_bf16 v[32:35], v[204:207], v[156:159], v[32:35]
	v_mfma_f32_16x16x32_bf16 v[24:27], v[196:199], v[164:167], v[24:27]
	v_mfma_f32_16x16x32_bf16 v[16:19], v[204:207], v[164:167], v[16:19]
	v_mfma_f32_16x16x32_bf16 v[8:11], v[196:199], v[172:175], v[8:11]
	v_mfma_f32_16x16x32_bf16 v[0:3], v[204:207], v[172:175], v[0:3]
	s_add_u32 s0, s0, 0x100
	s_addc_u32 s1, s1, 0
	s_add_u32 s70, s70, 0x100
	s_addc_u32 s71, s71, 0
	s_cmp_ge_u32 s72, s7
	s_mov_b32 s40, s72
	s_barrier
	s_cbranch_scc0 .LBB0_141
